# hot loop heads (GEMM K-loop, MLA and band attention loops) aligned to 64-byte boundaries
# baseline (speedup 1.0000x reference)
; template <bool BAND> DI void partialSM(f32x16& p0, f32x16& p1, float& m_reg, float& mn, float& alpha, bool masked, const LAS float* tb, float C) {
;     ...
;   const float CC = BAND ? 1.f : C;
;   const float THRP = 11.5f / CC;
;   float pmax = p0[0];
; #pragma unroll
;   for (int r = 1; r < 16; ++r) pmax = fmaxf(pmax, p0[r]);
; #pragma unroll
;   for (int r = 0; r < 16; ++r) pmax = fmaxf(pmax, p1[r]);
;   { auto rr = __builtin_amdgcn_permlane32_swap(__float_as_uint(pmax), __float_as_uint(pmax), false, false);
;     pmax = fmaxf(__uint_as_float(rr[0]), __uint_as_float(rr[1])); }
;   if (__builtin_expect(__all(pmax - m_reg <= THRP), 1)) { mn = m_reg; alpha = 1.f; }
;   else { mn = fmaxf(m_reg, pmax); alpha = __builtin_amdgcn_exp2f((m_reg - mn) * CC); m_reg = mn; }
;   const float mnC = -mn * CC;
; #pragma unroll
;   for (int r = 0; r < 16; ++r) p0[r] = fmaf(p0[r], CC, mnC);
; #pragma unroll
;   for (int r = 0; r < 16; ++r) p1[r] = fmaf(p1[r], CC, mnC);
; #pragma unroll
;   for (int r = 0; r < 16; ++r) p0[r] = __builtin_amdgcn_exp2f(p0[r]);
; template <bool BAND, int SD, bool ACT> DI void attn_unit_(const Unit& U, LAS char* lds, float C) {
;     ...
;   const int vb0 = (int)(uintptr_t)V_lds + v_rd_base(lane);
;   const int jb0 = 575 - U.qrel0 - 32 * wq - r32 + 4 * hi;
;   struct { bf16x8 vs0, vs1, ks0, ks1, kr; } sr_[SD];
;   const int ntr = U.nt, NT = (U.nt + 1) & ~1;
;   const unsigned vo0 = (unsigned)(sr * U.ldk + sc) * 2u, vo1 = (unsigned)((32 + sr) * U.ldk + sc) * 2u, vokr = (unsigned)(krr * 64 + krc) * 2u;
;   const size_t tstep = (size_t)64 * U.ldk * 2;
;     ...
;   f32x16 pA0, pA1, pB0, pB1; float mnA, mnB, alA = 1.f, alB = 1.f; bf16x8 pa0, pa1, pa2, pa3;
;   { u32x4 zz = {0u, 0u, 0u, 0u}; asm volatile("" : "+v"(zz)); pa0 = pa1 = pa2 = pa3 = __builtin_bit_cast(bf16x8, zz); }
;   constexpr int SE = 0, SO = SD - 1;
;   if (ACT && wid >= 4) __builtin_amdgcn_s_setprio(1);
;   SLOAD(SE, 0); if (SD == 2) SLOAD(SO, 1);
;   if (SD == 2) asm volatile("s_waitcnt vmcnt(%0)" ::"n"(BAND ? 4 : 5) : "memory"); else asm volatile("s_waitcnt vmcnt(0)" ::: "memory");
;   SWRITE(0, SE);
;   if (SD == 2) { if (2 < NT) SLOAD(SE, 2); } else SLOAD(SO, 1);
;   __syncthreads();
;   if (ACT) { qkt<NQ>(pA0, pA1, K_lds, KR_lds, qr, r32, hi); partialSM<BAND>(pA0, pA1, m_reg, mnA, alA, MASKED(0), T3 + jb0, C); }
;   SWAIT(); SWRITE(1, SO); __syncthreads();
;   for (int j = 1; j + 1 < NT; j += 2) {
.LBB0_280:
	v_and_b32_e32 v191, 63, v190
	s_nop 5
	v_lshlrev_b32_e32 v1, 4, v191
	v_lshlrev_b32_e32 v0, 3, v191
	v_and_b32_e32 v1, 0xc0, v1
	v_lshlrev_b32_e32 v2, 1, v191
	v_and_or_b32 v1, v0, 24, v1
	v_and_b32_e32 v2, 32, v2
	v_and_b32_e32 v0, 0x100, v0
	v_or3_b32 v219, v1, v2, v0
	v_max_f32_e32 v0, v65, v65
	v_max_f32_e32 v1, v64, v64
	v_max_f32_e32 v0, v1, v0
	v_max3_f32 v0, v0, v66, v67
	v_max3_f32 v0, v0, v62, v63
	v_max3_f32 v0, v0, v60, v61
	v_max3_f32 v0, v0, v56, v57
	v_max3_f32 v0, v0, v58, v59
	v_max3_f32 v0, v0, v54, v55
	v_max3_f32 v0, v0, v52, v53
	v_max3_f32 v0, v0, v48, v49
	v_max3_f32 v0, v0, v50, v51
	v_max3_f32 v0, v0, v74, v75
	v_max3_f32 v0, v0, v72, v73
	v_max3_f32 v0, v0, v70, v71
	v_max3_f32 v0, v0, v68, v69
	v_max3_f32 v0, v0, v76, v77
	v_max3_f32 v0, v0, v78, v79
	v_mov_b32_e32 v1, v0
	s_nop 1
	v_permlane32_swap_b32_e32 v0, v1
	v_max_f32_e32 v1, v1, v1
	v_max_f32_e32 v0, v0, v0
	s_and_b32 s18, s42, 0x3fffffc0
	v_max_f32_e32 v0, v0, v1
	s_lshl_b32 s18, s18, 2
	v_add_f32_e32 v1, 0x7149f2ca, v0
	s_mov_b32 s40, 0x41380000
	v_max_f32_e32 v0, 0xf149f2ca, v0
	s_add_i32 s20, s18, 0
	v_cmp_ge_f32_e32 vcc, s40, v1
	v_sub_f32_e32 v1, 0xf149f2ca, v0
	s_add_i32 s20, s20, 0x15000
	v_exp_f32_e32 v1, v1
	s_cmp_eq_u64 vcc, exec
	s_cselect_b64 vcc, -1, 0
	v_cndmask_b32_e32 v228, v0, v211, vcc
	v_cndmask_b32_e64 v227, v1, 1.0, vcc
	v_sub_f32_e32 v0, v64, v228
	v_sub_f32_e32 v1, v65, v228
	v_sub_f32_e32 v2, v66, v228
	v_sub_f32_e32 v3, v67, v228
	v_sub_f32_e32 v4, v62, v228
	v_sub_f32_e32 v5, v63, v228
	v_sub_f32_e32 v6, v60, v228
	v_sub_f32_e32 v7, v61, v228
	v_sub_f32_e32 v8, v56, v228
	v_sub_f32_e32 v9, v57, v228
	v_sub_f32_e32 v10, v58, v228
	v_sub_f32_e32 v11, v59, v228
	v_sub_f32_e32 v12, v54, v228
	v_sub_f32_e32 v13, v55, v228
	v_sub_f32_e32 v14, v52, v228
	v_sub_f32_e32 v15, v53, v228
	v_exp_f32_e32 v177, v0
	v_exp_f32_e32 v179, v1
	v_exp_f32_e32 v175, v2
	v_exp_f32_e32 v178, v3
	v_exp_f32_e32 v174, v4
	v_exp_f32_e32 v176, v5
	v_exp_f32_e32 v172, v6
	v_exp_f32_e32 v173, v7
	v_exp_f32_e32 v169, v8
	v_exp_f32_e32 v171, v9
	v_exp_f32_e32 v168, v10
	v_exp_f32_e32 v170, v11
	v_exp_f32_e32 v165, v12
	v_exp_f32_e32 v167, v13
	v_exp_f32_e32 v164, v14
	v_exp_f32_e32 v166, v15
	s_waitcnt vmcnt(4)
	v_add_u32_e32 v223, 0, v219
	v_sub_f32_e32 v65, v79, v228
	v_sub_f32_e32 v64, v78, v228
	v_sub_f32_e32 v67, v77, v228
	v_sub_f32_e32 v66, v76, v228
	v_sub_f32_e32 v69, v69, v228
	v_sub_f32_e32 v68, v68, v228
	v_sub_f32_e32 v71, v71, v228
	v_sub_f32_e32 v70, v70, v228
	v_sub_f32_e32 v73, v73, v228
	v_sub_f32_e32 v72, v72, v228
	v_sub_f32_e32 v75, v75, v228
	v_sub_f32_e32 v74, v74, v228
	v_sub_f32_e32 v77, v51, v228
	s_andn2_b64 vcc, exec, s[16:17]
	v_cmp_gt_u32_e64 s[42:43], 32, v191
	v_lshl_add_u32 v218, v80, 2, s20
	v_sub_f32_e32 v76, v50, v228
	v_sub_f32_e32 v79, v49, v228
	v_sub_f32_e32 v78, v48, v228
	v_mov_b32_e32 v15, 0
	s_waitcnt vmcnt(3)
	ds_write_b128 v224, v[44:47] offset:16384
	s_waitcnt vmcnt(2)
	ds_write_b128 v225, v[36:39] offset:16384
	s_waitcnt vmcnt(1)
	ds_write_b128 v226, v[40:43] offset:50176
	s_waitcnt vmcnt(0)
	ds_write_b128 v226, v[32:35] offset:58880
	s_waitcnt lgkmcnt(0)
	s_barrier
	s_cbranch_vccnz .LBB0_298
	v_add_u32_e32 v0, s44, v80
	s_add_i32 s16, 0, 0x4000
	v_sub_u32_e32 v0, v0, v216
	v_add_u32_e32 v230, s16, v219
	v_subrev_u32_e32 v0, s45, v0
	v_readlane_b32 s16, v254, 63
	v_mov_b32_e32 v220, 0
	v_lshl_add_u32 v229, v216, 2, s20
	v_lshl_add_u32 v231, v0, 2, s16
	s_mov_b32 s49, 4
	v_mov_b32_e32 v48, 0
	v_mov_b32_e32 v49, v220
	v_mov_b32_e32 v50, v220
	v_mov_b32_e32 v51, v220
	v_mov_b32_e32 v52, v220
	v_mov_b32_e32 v53, v220
	v_mov_b32_e32 v54, v220
	v_mov_b32_e32 v55, v220
	v_mov_b32_e32 v56, v220
	v_mov_b32_e32 v57, v220
	v_mov_b32_e32 v58, v220
	v_mov_b32_e32 v59, v220
	v_mov_b32_e32 v60, v220
	v_mov_b32_e32 v61, v220
	v_mov_b32_e32 v62, v220
	v_mov_b32_e32 v63, v220
	v_mov_b32_e32 v32, 0
	v_mov_b32_e32 v33, v220
	v_mov_b32_e32 v34, v220
	v_mov_b32_e32 v35, v220
	v_mov_b32_e32 v36, v220
	v_mov_b32_e32 v37, v220
	v_mov_b32_e32 v38, v220
	v_mov_b32_e32 v39, v220
	v_mov_b32_e32 v40, v220
	v_mov_b32_e32 v41, v220
	v_mov_b32_e32 v42, v220
	v_mov_b32_e32 v43, v220
	v_mov_b32_e32 v44, v220
	v_mov_b32_e32 v45, v220
	v_mov_b32_e32 v46, v220
	v_mov_b32_e32 v47, v220
	v_mov_b32_e32 v16, 0
	v_mov_b32_e32 v17, v220
	v_mov_b32_e32 v18, v220
	v_mov_b32_e32 v19, v220
	v_mov_b32_e32 v20, v220
	v_mov_b32_e32 v21, v220
	v_mov_b32_e32 v22, v220
	v_mov_b32_e32 v23, v220
	v_mov_b32_e32 v24, v220
	v_mov_b32_e32 v25, v220
	v_mov_b32_e32 v26, v220
	v_mov_b32_e32 v27, v220
	v_mov_b32_e32 v28, v220
	v_mov_b32_e32 v29, v220
	v_mov_b32_e32 v30, v220
	v_mov_b32_e32 v31, v220
	v_mov_b32_e32 v0, 0
	v_mov_b32_e32 v1, v220
	v_mov_b32_e32 v2, v220
	v_mov_b32_e32 v3, v220
	v_mov_b32_e32 v4, v220
	v_mov_b32_e32 v5, v220
	v_mov_b32_e32 v6, v220
	v_mov_b32_e32 v7, v220
	v_mov_b32_e32 v8, v220
	v_mov_b32_e32 v9, v220
	v_mov_b32_e32 v10, v220
	v_mov_b32_e32 v11, v220
	v_mov_b32_e32 v12, v220
	v_mov_b32_e32 v13, v220
	v_mov_b32_e32 v14, v220
	v_mov_b32_e32 v15, v220
	.p2align	6

; #define SWAIT() do { if (SD == 2) asm volatile("s_waitcnt vmcnt(%0)" ::"n"(BAND ? 4 : 5) : "memory"); else asm volatile("s_waitcnt vmcnt(0)" ::: "memory"); } while (0)
; template <bool BAND> DI void partialSM(f32x16& p0, f32x16& p1, float& m_reg, float& mn, float& alpha, bool masked, const LAS float* tb, float C) {
;     ...
;   const float mnC = -mn * CC;
; #pragma unroll
;   for (int r = 0; r < 16; ++r) p0[r] = fmaf(p0[r], CC, mnC);
; #pragma unroll
;   for (int r = 0; r < 16; ++r) p1[r] = fmaf(p1[r], CC, mnC);
; #pragma unroll
;   for (int r = 0; r < 16; ++r) p0[r] = __builtin_amdgcn_exp2f(p0[r]);
; template <bool BAND, int SD, bool ACT> DI void attn_unit_(const Unit& U, LAS char* lds, float C) {
;     ...
;   f32x16 pA0, pA1, pB0, pB1; float mnA, mnB, alA = 1.f, alB = 1.f; bf16x8 pa0, pa1, pa2, pa3;
;   { u32x4 zz = {0u, 0u, 0u, 0u}; asm volatile("" : "+v"(zz)); pa0 = pa1 = pa2 = pa3 = __builtin_bit_cast(bf16x8, zz); }
;   constexpr int SE = 0, SO = SD - 1;
;   if (ACT && wid >= 4) __builtin_amdgcn_s_setprio(1);
;   SLOAD(SE, 0); if (SD == 2) SLOAD(SO, 1);
;   if (SD == 2) asm volatile("s_waitcnt vmcnt(%0)" ::"n"(BAND ? 4 : 5) : "memory"); else asm volatile("s_waitcnt vmcnt(0)" ::: "memory");
;   SWRITE(0, SE);
;   if (SD == 2) { if (2 < NT) SLOAD(SE, 2); } else SLOAD(SO, 1);
;   __syncthreads();
;   if (ACT) { qkt<NQ>(pA0, pA1, K_lds, KR_lds, qr, r32, hi); partialSM<BAND>(pA0, pA1, m_reg, mnA, alA, MASKED(0), T3 + jb0, C); }
;   SWAIT(); SWRITE(1, SO); __syncthreads();
;   for (int j = 1; j + 1 < NT; j += 2) {
.LBB0_343:
	v_and_b32_e32 v195, 63, v52
	v_lshlrev_b32_e32 v54, 4, v195
	v_lshlrev_b32_e32 v52, 3, v195
	v_and_b32_e32 v54, 0xc0, v54
	v_lshlrev_b32_e32 v55, 1, v195
	v_and_or_b32 v54, v52, 24, v54
	v_and_b32_e32 v55, 32, v55
	v_and_b32_e32 v52, 0x100, v52
	v_or3_b32 v54, v54, v55, v52
	v_mul_f32_e32 v52, 0xbdd53b94, v203
	s_and_b32 s16, s34, 0x3fffffc0
	v_mov_b32_e32 v58, v52
	s_lshl_b32 s16, s16, 2
	v_fmamk_f32 v0, v0, 0x3dd53b94, v52
	v_fmamk_f32 v1, v1, 0x3dd53b94, v52
	v_fmamk_f32 v2, v2, 0x3dd53b94, v52
	v_fmamk_f32 v3, v3, 0x3dd53b94, v52
	v_fmamk_f32 v4, v4, 0x3dd53b94, v52
	v_fmamk_f32 v5, v5, 0x3dd53b94, v52
	v_fmamk_f32 v6, v6, 0x3dd53b94, v52
	v_fmamk_f32 v7, v7, 0x3dd53b94, v52
	v_fmamk_f32 v8, v8, 0x3dd53b94, v52
	v_fmamk_f32 v9, v9, 0x3dd53b94, v52
	v_fmamk_f32 v10, v10, 0x3dd53b94, v52
	v_fmamk_f32 v11, v11, 0x3dd53b94, v52
	v_fmamk_f32 v55, v12, 0x3dd53b94, v52
	v_fmamk_f32 v56, v13, 0x3dd53b94, v52
	v_fmamk_f32 v57, v14, 0x3dd53b94, v52
	v_fmac_f32_e32 v58, 0x3dd53b94, v15
	v_mul_u32_u24_e32 v53, 0x90, v198
	s_add_i32 s18, s16, 0
	v_exp_f32_e32 v110, v0
	v_exp_f32_e32 v111, v1
	v_exp_f32_e32 v108, v2
	v_exp_f32_e32 v109, v3
	v_exp_f32_e32 v106, v4
	v_exp_f32_e32 v107, v5
	v_exp_f32_e32 v72, v6
	v_exp_f32_e32 v73, v7
	v_exp_f32_e32 v66, v8
	v_exp_f32_e32 v67, v9
	v_exp_f32_e32 v64, v10
	v_exp_f32_e32 v65, v11
	s_add_i32 s16, 0, 0x12c00
	v_exp_f32_e32 v68, v55
	v_exp_f32_e32 v69, v56
	v_exp_f32_e32 v70, v57
	v_exp_f32_e32 v71, v58
	v_pk_fma_f32 v[196:197], v[16:17], s[38:39], v[52:53] op_sel_hi:[1,0,0]
	s_waitcnt vmcnt(0)
	v_add_u32_e32 v0, s16, v194
	v_add_u32_e32 v16, s16, v53
	s_add_i32 s16, 0, 0x4000
	v_mov_b32_e32 v14, v113
	v_mov_b32_e32 v15, v113
	s_add_i32 s33, s37, -1
	s_add_i32 s18, s18, 0x15000
	v_add_u32_e32 v216, 0, v54
	s_add_i32 s37, s37, 1
	v_pk_fma_f32 v[164:165], v[30:31], s[38:39], v[52:53] op_sel_hi:[1,0,0]
	v_pk_fma_f32 v[166:167], v[28:29], s[38:39], v[52:53] op_sel_hi:[1,0,0]
	v_pk_fma_f32 v[168:169], v[26:27], s[38:39], v[52:53] op_sel_hi:[1,0,0]
	v_pk_fma_f32 v[170:171], v[24:25], s[38:39], v[52:53] op_sel_hi:[1,0,0]
	v_pk_fma_f32 v[172:173], v[22:23], s[38:39], v[52:53] op_sel_hi:[1,0,0]
	v_pk_fma_f32 v[174:175], v[20:21], s[38:39], v[52:53] op_sel_hi:[1,0,0]
	v_pk_fma_f32 v[178:179], v[18:19], s[38:39], v[52:53] op_sel_hi:[1,0,0]
	s_waitcnt vmcnt(4)
	ds_write_b128 v204, v[32:35] offset:16384
	s_waitcnt vmcnt(3)
	ds_write_b128 v205, v[36:39] offset:16384
	s_waitcnt vmcnt(2)
	ds_write_b128 v206, v[40:43] offset:50176
	s_waitcnt vmcnt(1)
	ds_write_b128 v206, v[44:47] offset:58880
	s_waitcnt vmcnt(0)
	ds_write_b128 v0, v[48:51]
	v_add_u32_e32 v202, s16, v54
	v_mov_b32_e32 v0, v113
	v_mov_b32_e32 v1, v113
	v_mov_b32_e32 v2, v113
	v_mov_b32_e32 v3, v113
	v_mov_b32_e32 v4, v113
	v_mov_b32_e32 v5, v113
	v_mov_b32_e32 v6, v113
	v_mov_b32_e32 v7, v113
	v_mov_b32_e32 v8, v113
	v_mov_b32_e32 v9, v113
	v_mov_b32_e32 v10, v113
	v_mov_b32_e32 v11, v113
	v_mov_b32_e32 v12, v113
	v_mov_b32_e32 v13, v113
	v_add_u32_e32 v218, v16, v190
	v_mov_b64_e32 v[62:63], v[14:15]
	v_mov_b64_e32 v[46:47], v[14:15]
	v_mov_b64_e32 v[30:31], v[14:15]
	v_mov_b32_e32 v115, v113
	s_add_i32 s34, s35, 0xfffe7960
	s_mov_b32 s35, 3
	s_and_b32 s19, s37, 0x7ffffffe
	v_cmp_gt_u32_e64 s[42:43], 32, v195
	v_lshl_add_u32 v200, v198, 2, s18
	v_mov_b32_e32 v201, 0
	v_mov_b64_e32 v[60:61], v[12:13]
	v_mov_b64_e32 v[58:59], v[10:11]
	v_mov_b64_e32 v[56:57], v[8:9]
	v_mov_b64_e32 v[54:55], v[6:7]
	v_mov_b64_e32 v[52:53], v[4:5]
	v_mov_b64_e32 v[50:51], v[2:3]
	v_mov_b64_e32 v[48:49], v[0:1]
	v_mov_b64_e32 v[44:45], v[12:13]
	v_mov_b64_e32 v[42:43], v[10:11]
	v_mov_b64_e32 v[40:41], v[8:9]
	v_mov_b64_e32 v[38:39], v[6:7]
	v_mov_b64_e32 v[36:37], v[4:5]
	v_mov_b64_e32 v[34:35], v[2:3]
	v_mov_b64_e32 v[32:33], v[0:1]
	v_mov_b64_e32 v[28:29], v[12:13]
	v_mov_b64_e32 v[26:27], v[10:11]
	v_mov_b64_e32 v[24:25], v[8:9]
	v_mov_b64_e32 v[22:23], v[6:7]
	v_mov_b64_e32 v[20:21], v[4:5]
	v_mov_b64_e32 v[18:19], v[2:3]
	v_mov_b64_e32 v[16:17], v[0:1]
	s_waitcnt lgkmcnt(0)
	s_barrier
	.p2align	6

; #define PG8_STAGE(bufoff, gbase, voff) do { _Pragma("unroll") for (int _i = 0; _i < 2; ++_i) \
;         __builtin_amdgcn_global_load_lds((const unsigned*)((const char*)(gbase) + (voff)[_i]), (PG8_LAS unsigned*)(lds + (bufoff) + ldsw + _i * 8192), 16, 0, 0); } while (0)
; #define PG8_LDA(dst, b, h) do { _Pragma("unroll") for (int m = 0; m < 4; ++m) _Pragma("unroll") for (int k = 0; k < 2; ++k) dst[m][k] = *(const PG8_LAS bf16x8*)(lds + PG8_SA(b, h) + aoff + m * 2048 + k * 1024); } while (0)
; #define PG8_LDB(dst, b, h) do { _Pragma("unroll") for (int n = 0; n < 2; ++n) _Pragma("unroll") for (int k = 0; k < 2; ++k) dst[n][k] = *(const PG8_LAS bf16x8*)(lds + PG8_SB(b, h) + boff + n * 2048 + k * 1024); } while (0)
; #define PG8_MMA(ai, bj, At, Bt) do { __builtin_amdgcn_s_setprio(1); _Pragma("unroll") for (int m = 0; m < 4; ++m) _Pragma("unroll") for (int n = 0; n < 2; ++n) _Pragma("unroll") for (int k = 0; k < 2; ++k) \
;         acc[ai][bj][m][n] = __builtin_amdgcn_mfma_f32_16x16x32_bf16(Bt[n][k], At[m][k], acc[ai][bj][m][n], 0, 0, 0); __builtin_amdgcn_s_setprio(0); } while (0)
; #define PG8_WAIT_V(n) asm volatile("s_waitcnt vmcnt(" #n ")" ::: "memory")
; template <class Epi, class Sched, bool ALIGN_EPI = false, bool SP2 = false>
; __device__ __forceinline__ void gemm_phase(PG8_LAS unsigned char* lds, const Gemm g, const Sched& S, const Epi& E) {
;     ...
;             PG8_LDB(B0, 0, 0); PG8_LDB(B1, 0, 1); PG8_SCHED; PG8_LDA(At, 0, 0); PG8_STAGE(PG8_SA(1, 1), a1 + hstepA, voffA);
;             PG8_WAIT_V(8); PG8_WAIT_L(0); PG8_BAR; PG8_MMA(0, 0, At, B0); PG8_MMA(0, 1, At, B1); PG8_BAR; PG8_SCHED;
;             PG8_LDA(At, 0, 1); PG8_STAGE(PG8_SB(0, 0), b2, voffB); PG8_STAGE(PG8_SB(0, 1), b2 + hstep, voffB); PG8_STAGE(PG8_SA(0, 0), a2, voffA);
;             PG8_WAIT_V(8); PG8_WAIT_L(0); PG8_BAR; PG8_MMA(1, 0, At, B0); PG8_MMA(1, 1, At, B1); PG8_BAR; PG8_SCHED;
;             PG8_LDB(B0, 1, 0); PG8_LDB(B1, 1, 1); PG8_SCHED; PG8_LDA(At, 1, 0); PG8_STAGE(PG8_SA(0, 1), a2 + hstepA, voffA);
;             PG8_WAIT_V(8); PG8_WAIT_L(0); PG8_BAR; PG8_MMA(0, 0, At, B0); PG8_MMA(0, 1, At, B1); PG8_BAR; PG8_SCHED;
;             PG8_LDA(At, 1, 1); PG8_STAGE(PG8_SB(1, 0), b3, voffB); PG8_STAGE(PG8_SB(1, 1), b3 + hstep, voffB); PG8_STAGE(PG8_SA(1, 0), a3, voffA);
;             PG8_WAIT_V(8); PG8_WAIT_L(0); PG8_BAR; PG8_MMA(1, 0, At, B0); PG8_MMA(1, 1, At, B1); PG8_BAR; PG8_SCHED;
.Lpw1_done:
	s_waitcnt lgkmcnt(0)
	s_barrier
	s_setprio 1
	s_waitcnt lgkmcnt(0)
	v_mfma_f32_16x16x32_bf16 v[60:63], v[130:133], v[188:191], 0
	v_mfma_f32_16x16x32_bf16 v[56:59], v[138:141], v[188:191], 0
	v_mfma_f32_16x16x32_bf16 v[44:47], v[130:133], v[196:199], 0
	v_mfma_f32_16x16x32_bf16 v[40:43], v[138:141], v[196:199], 0
	v_mfma_f32_16x16x32_bf16 v[28:31], v[130:133], v[204:207], 0
	v_mfma_f32_16x16x32_bf16 v[24:27], v[138:141], v[204:207], 0
	v_mfma_f32_16x16x32_bf16 v[12:15], v[130:133], v[220:223], 0
	v_mfma_f32_16x16x32_bf16 v[8:11], v[138:141], v[220:223], 0
	v_mfma_f32_16x16x32_bf16 v[60:63], v[134:137], v[192:195], v[60:63]
	v_mfma_f32_16x16x32_bf16 v[56:59], v[154:157], v[192:195], v[56:59]
	v_mfma_f32_16x16x32_bf16 v[44:47], v[134:137], v[200:203], v[44:47]
	v_mfma_f32_16x16x32_bf16 v[40:43], v[154:157], v[200:203], v[40:43]
	v_mfma_f32_16x16x32_bf16 v[28:31], v[134:137], v[216:219], v[28:31]
	v_mfma_f32_16x16x32_bf16 v[24:27], v[154:157], v[216:219], v[24:27]
	v_mfma_f32_16x16x32_bf16 v[12:15], v[134:137], v[224:227], v[12:15]
	v_mfma_f32_16x16x32_bf16 v[8:11], v[154:157], v[224:227], v[8:11]
	s_setprio 0
	s_setprio 1
	v_mfma_f32_16x16x32_bf16 v[52:55], v[158:161], v[188:191], 0
	v_mfma_f32_16x16x32_bf16 v[48:51], v[166:169], v[188:191], 0
	v_mfma_f32_16x16x32_bf16 v[36:39], v[158:161], v[196:199], 0
	v_mfma_f32_16x16x32_bf16 v[32:35], v[166:169], v[196:199], 0
	v_mfma_f32_16x16x32_bf16 v[20:23], v[158:161], v[204:207], 0
	v_mfma_f32_16x16x32_bf16 v[16:19], v[166:169], v[204:207], 0
	v_mfma_f32_16x16x32_bf16 v[4:7], v[158:161], v[220:223], 0
	v_mfma_f32_16x16x32_bf16 v[0:3], v[166:169], v[220:223], 0
	v_mfma_f32_16x16x32_bf16 v[52:55], v[162:165], v[192:195], v[52:55]
	v_mfma_f32_16x16x32_bf16 v[48:51], v[170:173], v[192:195], v[48:51]
	v_mfma_f32_16x16x32_bf16 v[36:39], v[162:165], v[200:203], v[36:39]
	v_mfma_f32_16x16x32_bf16 v[32:35], v[170:173], v[200:203], v[32:35]
	v_mfma_f32_16x16x32_bf16 v[20:23], v[162:165], v[216:219], v[20:23]
	v_mfma_f32_16x16x32_bf16 v[16:19], v[170:173], v[216:219], v[16:19]
	v_mfma_f32_16x16x32_bf16 v[4:7], v[162:165], v[224:227], v[4:7]
	v_mfma_f32_16x16x32_bf16 v[0:3], v[170:173], v[224:227], v[0:3]
	s_setprio 0
	s_barrier
	s_add_i32 s22, 0, 0x18000
	v_add_u32_e32 v112, s22, v176
	s_add_i32 s23, 0, 0x1c000
	ds_read_b128 v[130:133], v112
	ds_read_b128 v[134:137], v112 offset:1024
	ds_read_b128 v[138:141], v112 offset:2048
	ds_read_b128 v[154:157], v112 offset:3072
	v_add_u32_e32 v112, s23, v176
	ds_read_b128 v[158:161], v112
	ds_read_b128 v[162:165], v112 offset:1024
	ds_read_b128 v[166:169], v112 offset:2048
	ds_read_b128 v[170:173], v112 offset:3072
	s_add_u32 s24, s24, s12
	s_addc_u32 s25, s25, s13
	s_mov_b32 m0, s50
	v_lshl_add_u64 v[232:233], s[24:25], 0, v[142:143]
	ds_read_b128 v[188:191], v177 offset:32768
	ds_read_b128 v[192:195], v177 offset:33792
	ds_read_b128 v[196:199], v177 offset:34816
	ds_read_b128 v[200:203], v177 offset:35840
	ds_read_b128 v[204:207], v177 offset:36864
	ds_read_b128 v[216:219], v177 offset:37888
	ds_read_b128 v[220:223], v177 offset:38912
	ds_read_b128 v[224:227], v177 offset:39936
	global_load_lds_dwordx4 v[232:233], off
	v_lshl_add_u64 v[232:233], s[24:25], 0, v[146:147]
	s_mov_b32 m0, s51
	s_nop 0
	global_load_lds_dwordx4 v[232:233], off
	s_waitcnt vmcnt(8)
	s_waitcnt lgkmcnt(0)
	s_barrier
	s_setprio 1
	s_waitcnt lgkmcnt(0)
	v_mfma_f32_16x16x32_bf16 v[126:129], v[130:133], v[188:191], v[126:129]
	v_mfma_f32_16x16x32_bf16 v[122:125], v[138:141], v[188:191], v[122:125]
	v_mfma_f32_16x16x32_bf16 v[108:111], v[130:133], v[196:199], v[108:111]
	v_mfma_f32_16x16x32_bf16 v[104:107], v[138:141], v[196:199], v[104:107]
	v_mfma_f32_16x16x32_bf16 v[92:95], v[130:133], v[204:207], v[92:95]
	v_mfma_f32_16x16x32_bf16 v[88:91], v[138:141], v[204:207], v[88:91]
	v_mfma_f32_16x16x32_bf16 v[76:79], v[130:133], v[220:223], v[76:79]
	v_mfma_f32_16x16x32_bf16 v[72:75], v[138:141], v[220:223], v[72:75]
	v_mfma_f32_16x16x32_bf16 v[126:129], v[134:137], v[192:195], v[126:129]
	v_mfma_f32_16x16x32_bf16 v[122:125], v[154:157], v[192:195], v[122:125]
	v_mfma_f32_16x16x32_bf16 v[108:111], v[134:137], v[200:203], v[108:111]
	v_mfma_f32_16x16x32_bf16 v[104:107], v[154:157], v[200:203], v[104:107]
	v_mfma_f32_16x16x32_bf16 v[92:95], v[134:137], v[216:219], v[92:95]
	v_mfma_f32_16x16x32_bf16 v[88:91], v[154:157], v[216:219], v[88:91]
	v_mfma_f32_16x16x32_bf16 v[76:79], v[134:137], v[224:227], v[76:79]
	v_mfma_f32_16x16x32_bf16 v[72:75], v[154:157], v[224:227], v[72:75]
	s_setprio 0
	s_setprio 1
	v_mfma_f32_16x16x32_bf16 v[118:121], v[158:161], v[188:191], v[118:121]
	v_mfma_f32_16x16x32_bf16 v[114:117], v[166:169], v[188:191], v[114:117]
	v_mfma_f32_16x16x32_bf16 v[100:103], v[158:161], v[196:199], v[100:103]
	v_mfma_f32_16x16x32_bf16 v[96:99], v[166:169], v[196:199], v[96:99]
	v_mfma_f32_16x16x32_bf16 v[84:87], v[158:161], v[204:207], v[84:87]
	v_mfma_f32_16x16x32_bf16 v[80:83], v[166:169], v[204:207], v[80:83]
	v_mfma_f32_16x16x32_bf16 v[68:71], v[158:161], v[220:223], v[68:71]
	v_mfma_f32_16x16x32_bf16 v[64:67], v[166:169], v[220:223], v[64:67]
	v_mfma_f32_16x16x32_bf16 v[118:121], v[162:165], v[192:195], v[118:121]
	v_mfma_f32_16x16x32_bf16 v[114:117], v[170:173], v[192:195], v[114:117]
	v_mfma_f32_16x16x32_bf16 v[100:103], v[162:165], v[200:203], v[100:103]
	v_mfma_f32_16x16x32_bf16 v[96:99], v[170:173], v[200:203], v[96:99]
	v_mfma_f32_16x16x32_bf16 v[84:87], v[162:165], v[216:219], v[84:87]
	v_mfma_f32_16x16x32_bf16 v[80:83], v[170:173], v[216:219], v[80:83]
	v_mfma_f32_16x16x32_bf16 v[68:71], v[162:165], v[224:227], v[68:71]
	v_mfma_f32_16x16x32_bf16 v[64:67], v[170:173], v[224:227], v[64:67]
	s_setprio 0
	s_barrier
; #define PG8_STAGE(bufoff, gbase, voff) do { _Pragma("unroll") for (int _i = 0; _i < 2; ++_i) \
;         __builtin_amdgcn_global_load_lds((const unsigned*)((const char*)(gbase) + (voff)[_i]), (PG8_LAS unsigned*)(lds + (bufoff) + ldsw + _i * 8192), 16, 0, 0); } while (0)
; #define PG8_LDA(dst, b, h) do { _Pragma("unroll") for (int m = 0; m < 4; ++m) _Pragma("unroll") for (int k = 0; k < 2; ++k) dst[m][k] = *(const PG8_LAS bf16x8*)(lds + PG8_SA(b, h) + aoff + m * 2048 + k * 1024); } while (0)
; #define PG8_MMA(ai, bj, At, Bt) do { __builtin_amdgcn_s_setprio(1); _Pragma("unroll") for (int m = 0; m < 4; ++m) _Pragma("unroll") for (int n = 0; n < 2; ++n) _Pragma("unroll") for (int k = 0; k < 2; ++k) \
;         acc[ai][bj][m][n] = __builtin_amdgcn_mfma_f32_16x16x32_bf16(Bt[n][k], At[m][k], acc[ai][bj][m][n], 0, 0, 0); __builtin_amdgcn_s_setprio(0); } while (0)
; #define PG8_WAIT_V(n) asm volatile("s_waitcnt vmcnt(" #n ")" ::: "memory")
; #define PG8_WAIT_L(n) asm volatile("s_waitcnt lgkmcnt(" #n ")" ::: "memory")
; #define PG8_BAR __builtin_amdgcn_s_barrier()
; #define PG8_SCHED __builtin_amdgcn_sched_barrier(0)
; template <class Epi, class Sched, bool ALIGN_EPI = false, bool SP2 = false>
; __device__ __forceinline__ void gemm_phase(PG8_LAS unsigned char* lds, const Gemm g, const Sched& S, const Epi& E) {
;     ...
;             PG8_LDA(At, 1, 1); PG8_STAGE(PG8_SB(1, 0), b3, voffB); PG8_STAGE(PG8_SB(1, 1), b3 + hstep, voffB); PG8_STAGE(PG8_SA(1, 0), a3, voffA);
;             PG8_WAIT_V(8); PG8_WAIT_L(0); PG8_BAR; PG8_MMA(1, 0, At, B0); PG8_MMA(1, 1, At, B1); PG8_BAR; PG8_SCHED;
	s_add_i32 s22, s22, s39
	v_lshl_add_u64 v[174:175], v[174:175], 0, s[30:31]
	s_mov_b32 m0, s22
	ds_read_b128 v[188:191], v177 offset:49152
	ds_read_b128 v[192:195], v177 offset:50176
	ds_read_b128 v[196:199], v177 offset:51200
	ds_read_b128 v[200:203], v177 offset:52224
	ds_read_b128 v[204:207], v177 offset:53248
	ds_read_b128 v[216:219], v177 offset:54272
	ds_read_b128 v[220:223], v177 offset:55296
	ds_read_b128 v[224:227], v177 offset:56320
	global_load_lds_dwordx4 v[174:175], off
	v_lshl_add_u64 v[174:175], v[178:179], 0, s[30:31]
	s_add_i32 m0, s22, 0x2000
	s_add_i32 s22, s23, s39
	global_load_lds_dwordx4 v[174:175], off
	v_lshl_add_u64 v[174:175], v[212:213], 0, s[30:31]
	s_mov_b32 m0, s22
	s_nop 0
	global_load_lds_dwordx4 v[174:175], off
	v_lshl_add_u64 v[174:175], v[214:215], 0, s[30:31]
	s_add_i32 m0, s22, 0x2000
	s_nop 0
	global_load_lds_dwordx4 v[174:175], off
	v_lshl_add_u64 v[174:175], v[228:229], 0, s[30:31]
	s_mov_b32 m0, s57
	s_nop 0
	global_load_lds_dwordx4 v[174:175], off
	v_lshl_add_u64 v[174:175], v[230:231], 0, s[30:31]
	s_mov_b32 m0, s58
	s_nop 0
	global_load_lds_dwordx4 v[174:175], off
	s_waitcnt vmcnt(8)
	s_waitcnt lgkmcnt(0)
	s_barrier
	s_setprio 1
	s_waitcnt lgkmcnt(0)
	v_mfma_f32_16x16x32_bf16 v[60:63], v[130:133], v[188:191], v[60:63]
	v_mfma_f32_16x16x32_bf16 v[56:59], v[138:141], v[188:191], v[56:59]
	v_mfma_f32_16x16x32_bf16 v[44:47], v[130:133], v[196:199], v[44:47]
	v_mfma_f32_16x16x32_bf16 v[40:43], v[138:141], v[196:199], v[40:43]
	v_mfma_f32_16x16x32_bf16 v[28:31], v[130:133], v[204:207], v[28:31]
	v_mfma_f32_16x16x32_bf16 v[24:27], v[138:141], v[204:207], v[24:27]
	v_mfma_f32_16x16x32_bf16 v[12:15], v[130:133], v[220:223], v[12:15]
	v_mfma_f32_16x16x32_bf16 v[8:11], v[138:141], v[220:223], v[8:11]
	v_mfma_f32_16x16x32_bf16 v[60:63], v[134:137], v[192:195], v[60:63]
	v_mfma_f32_16x16x32_bf16 v[56:59], v[154:157], v[192:195], v[56:59]
	v_mfma_f32_16x16x32_bf16 v[44:47], v[134:137], v[200:203], v[44:47]
	v_mfma_f32_16x16x32_bf16 v[40:43], v[154:157], v[200:203], v[40:43]
	v_mfma_f32_16x16x32_bf16 v[28:31], v[134:137], v[216:219], v[28:31]
	v_mfma_f32_16x16x32_bf16 v[24:27], v[154:157], v[216:219], v[24:27]
	v_mfma_f32_16x16x32_bf16 v[12:15], v[134:137], v[224:227], v[12:15]
	v_mfma_f32_16x16x32_bf16 v[8:11], v[154:157], v[224:227], v[8:11]
	s_setprio 0
	s_setprio 1
	v_mfma_f32_16x16x32_bf16 v[52:55], v[158:161], v[188:191], v[52:55]
	v_mfma_f32_16x16x32_bf16 v[48:51], v[166:169], v[188:191], v[48:51]
	v_mfma_f32_16x16x32_bf16 v[36:39], v[158:161], v[196:199], v[36:39]
	v_mfma_f32_16x16x32_bf16 v[32:35], v[166:169], v[196:199], v[32:35]
	v_mfma_f32_16x16x32_bf16 v[20:23], v[158:161], v[204:207], v[20:23]
	v_mfma_f32_16x16x32_bf16 v[16:19], v[166:169], v[204:207], v[16:19]
	v_mfma_f32_16x16x32_bf16 v[4:7], v[158:161], v[220:223], v[4:7]
	v_mfma_f32_16x16x32_bf16 v[0:3], v[166:169], v[220:223], v[0:3]
	v_mfma_f32_16x16x32_bf16 v[52:55], v[162:165], v[192:195], v[52:55]
	v_mfma_f32_16x16x32_bf16 v[48:51], v[170:173], v[192:195], v[48:51]
	v_mfma_f32_16x16x32_bf16 v[36:39], v[162:165], v[200:203], v[36:39]
	v_mfma_f32_16x16x32_bf16 v[32:35], v[170:173], v[200:203], v[32:35]
	v_mfma_f32_16x16x32_bf16 v[20:23], v[162:165], v[216:219], v[20:23]
	v_mfma_f32_16x16x32_bf16 v[16:19], v[170:173], v[216:219], v[16:19]
	v_mfma_f32_16x16x32_bf16 v[4:7], v[162:165], v[224:227], v[4:7]
	v_mfma_f32_16x16x32_bf16 v[0:3], v[170:173], v[224:227], v[0:3]
	s_setprio 0
	s_barrier
	s_add_u32 s44, s44, 0x100
	s_addc_u32 s45, s45, 0
	s_add_u32 s21, s21, 0x100
	s_addc_u32 s40, s40, 0
	s_cmp_ge_i32 s41, s62
	s_mov_b32 s24, s41
	s_cbranch_scc1 .Lk_exit
	.p2align	6
